# prologue pool fold: all 96 loads of an item in flight (was 8 serialized batches)
# speedup vs baseline: 1.0014x; 1.0014x over previous
.LBB0_1175:
	s_mov_b32 s42, s39
	s_mov_b32 s43, s40
	s_mov_b32 s26, s31
	s_mov_b32 s27, s38
	v_readfirstlane_b32 s34, v0
	v_readfirstlane_b32 s35, v1
	v_lshlrev_b32_e32 v3, 2, v244
	s_nop 3
	s_add_u32 s34, s34, 0x101000
	s_addc_u32 s35, s35, 0
	global_load_dwordx4 v[76:79], v33, s[42:43]
	global_load_dwordx4 v[80:83], v33, s[42:43] offset:16
	global_load_dwordx4 v[84:87], v33, s[42:43] offset:32
	global_load_dwordx4 v[88:91], v33, s[42:43] offset:48
	global_load_dwordx4 v[92:95], v33, s[42:43] offset:64
	global_load_dwordx4 v[96:99], v33, s[42:43] offset:80
	global_load_dwordx4 v[100:103], v33, s[42:43] offset:96
	global_load_dwordx4 v[104:107], v33, s[42:43] offset:112
	global_load_dwordx4 v[108:111], v33, s[42:43] offset:128
	global_load_dwordx4 v[112:115], v33, s[42:43] offset:144
	global_load_dwordx4 v[116:119], v33, s[42:43] offset:160
	global_load_dwordx4 v[120:123], v33, s[42:43] offset:176
	global_load_dwordx4 v[124:127], v33, s[42:43] offset:192
	global_load_dwordx4 v[128:131], v33, s[42:43] offset:208
	global_load_dwordx4 v[132:135], v33, s[42:43] offset:224
	global_load_dwordx4 v[136:139], v33, s[42:43] offset:240
	global_load_dwordx4 v[140:143], v33, s[26:27]
	global_load_dwordx4 v[144:147], v33, s[26:27] offset:16
	global_load_dwordx4 v[148:151], v33, s[26:27] offset:32
	global_load_dwordx4 v[152:155], v33, s[26:27] offset:48
	global_load_dwordx4 v[156:159], v33, s[26:27] offset:64
	global_load_dwordx4 v[160:163], v33, s[26:27] offset:80
	global_load_dwordx4 v[164:167], v33, s[26:27] offset:96
	global_load_dwordx4 v[168:171], v33, s[26:27] offset:112
	global_load_dwordx4 v[172:175], v33, s[26:27] offset:128
	global_load_dwordx4 v[184:187], v33, s[26:27] offset:144
	global_load_dwordx4 v[188:191], v33, s[26:27] offset:160
	global_load_dwordx4 v[192:195], v33, s[26:27] offset:176
	global_load_dwordx4 v[196:199], v33, s[26:27] offset:192
	global_load_dwordx4 v[200:203], v33, s[26:27] offset:208
	global_load_dwordx4 v[204:207], v33, s[26:27] offset:224
	global_load_dwordx4 v[208:211], v33, s[26:27] offset:240
	global_load_dword v4, v3, s[34:35] offset:-4096
	global_load_dword v5, v3, s[34:35]
	s_add_u32 s34, s34, 0x2000
	s_addc_u32 s35, s35, 0
	global_load_dword v6, v3, s[34:35] offset:-4096
	global_load_dword v7, v3, s[34:35]
	s_add_u32 s34, s34, 0x2000
	s_addc_u32 s35, s35, 0
	global_load_dword v8, v3, s[34:35] offset:-4096
	global_load_dword v9, v3, s[34:35]
	s_add_u32 s34, s34, 0x2000
	s_addc_u32 s35, s35, 0
	global_load_dword v10, v3, s[34:35] offset:-4096
	global_load_dword v11, v3, s[34:35]
	s_add_u32 s34, s34, 0x2000
	s_addc_u32 s35, s35, 0
	global_load_dword v12, v3, s[34:35] offset:-4096
	global_load_dword v13, v3, s[34:35]
	s_add_u32 s34, s34, 0x2000
	s_addc_u32 s35, s35, 0
	global_load_dword v14, v3, s[34:35] offset:-4096
	global_load_dword v15, v3, s[34:35]
	s_add_u32 s34, s34, 0x2000
	s_addc_u32 s35, s35, 0
	global_load_dword v16, v3, s[34:35] offset:-4096
	global_load_dword v17, v3, s[34:35]
	s_add_u32 s34, s34, 0x2000
	s_addc_u32 s35, s35, 0
	global_load_dword v18, v3, s[34:35] offset:-4096
	global_load_dword v19, v3, s[34:35]
	s_add_u32 s34, s34, 0x2000
	s_addc_u32 s35, s35, 0
	global_load_dword v20, v3, s[34:35] offset:-4096
	global_load_dword v21, v3, s[34:35]
	s_add_u32 s34, s34, 0x2000
	s_addc_u32 s35, s35, 0
	global_load_dword v22, v3, s[34:35] offset:-4096
	global_load_dword v23, v3, s[34:35]
	s_add_u32 s34, s34, 0x2000
	s_addc_u32 s35, s35, 0
	global_load_dword v24, v3, s[34:35] offset:-4096
	global_load_dword v25, v3, s[34:35]
	s_add_u32 s34, s34, 0x2000
	s_addc_u32 s35, s35, 0
	global_load_dword v26, v3, s[34:35] offset:-4096
	global_load_dword v27, v3, s[34:35]
	s_add_u32 s34, s34, 0x2000
	s_addc_u32 s35, s35, 0
	global_load_dword v28, v3, s[34:35] offset:-4096
	global_load_dword v29, v3, s[34:35]
	s_add_u32 s34, s34, 0x2000
	s_addc_u32 s35, s35, 0
	global_load_dword v30, v3, s[34:35] offset:-4096
	global_load_dword v31, v3, s[34:35]
	s_add_u32 s34, s34, 0x2000
	s_addc_u32 s35, s35, 0
	global_load_dword v40, v3, s[34:35] offset:-4096
	global_load_dword v41, v3, s[34:35]
	s_add_u32 s34, s34, 0x2000
	s_addc_u32 s35, s35, 0
	global_load_dword v42, v3, s[34:35] offset:-4096
	global_load_dword v43, v3, s[34:35]
	s_add_u32 s34, s34, 0x2000
	s_addc_u32 s35, s35, 0
	global_load_dword v44, v3, s[34:35] offset:-4096
	global_load_dword v45, v3, s[34:35]
	s_add_u32 s34, s34, 0x2000
	s_addc_u32 s35, s35, 0
	global_load_dword v46, v3, s[34:35] offset:-4096
	global_load_dword v47, v3, s[34:35]
	s_add_u32 s34, s34, 0x2000
	s_addc_u32 s35, s35, 0
	global_load_dword v48, v3, s[34:35] offset:-4096
	global_load_dword v49, v3, s[34:35]
	s_add_u32 s34, s34, 0x2000
	s_addc_u32 s35, s35, 0
	global_load_dword v50, v3, s[34:35] offset:-4096
	global_load_dword v51, v3, s[34:35]
	s_add_u32 s34, s34, 0x2000
	s_addc_u32 s35, s35, 0
	global_load_dword v52, v3, s[34:35] offset:-4096
	global_load_dword v53, v3, s[34:35]
	s_add_u32 s34, s34, 0x2000
	s_addc_u32 s35, s35, 0
	global_load_dword v54, v3, s[34:35] offset:-4096
	global_load_dword v55, v3, s[34:35]
	s_add_u32 s34, s34, 0x2000
	s_addc_u32 s35, s35, 0
	global_load_dword v56, v3, s[34:35] offset:-4096
	global_load_dword v57, v3, s[34:35]
	s_add_u32 s34, s34, 0x2000
	s_addc_u32 s35, s35, 0
	global_load_dword v58, v3, s[34:35] offset:-4096
	global_load_dword v59, v3, s[34:35]
	s_add_u32 s34, s34, 0x2000
	s_addc_u32 s35, s35, 0
	global_load_dword v60, v3, s[34:35] offset:-4096
	global_load_dword v61, v3, s[34:35]
	s_add_u32 s34, s34, 0x2000
	s_addc_u32 s35, s35, 0
	global_load_dword v62, v3, s[34:35] offset:-4096
	global_load_dword v63, v3, s[34:35]
	s_add_u32 s34, s34, 0x2000
	s_addc_u32 s35, s35, 0
	global_load_dword v64, v3, s[34:35] offset:-4096
	global_load_dword v65, v3, s[34:35]
	s_add_u32 s34, s34, 0x2000
	s_addc_u32 s35, s35, 0
	global_load_dword v66, v3, s[34:35] offset:-4096
	global_load_dword v67, v3, s[34:35]
	s_add_u32 s34, s34, 0x2000
	s_addc_u32 s35, s35, 0
	global_load_dword v68, v3, s[34:35] offset:-4096
	global_load_dword v69, v3, s[34:35]
	s_add_u32 s34, s34, 0x2000
	s_addc_u32 s35, s35, 0
	global_load_dword v70, v3, s[34:35] offset:-4096
	global_load_dword v71, v3, s[34:35]
	s_add_u32 s34, s34, 0x2000
	s_addc_u32 s35, s35, 0
	global_load_dword v72, v3, s[34:35] offset:-4096
	global_load_dword v73, v3, s[34:35]
	s_add_u32 s34, s34, 0x2000
	s_addc_u32 s35, s35, 0
	global_load_dword v74, v3, s[34:35] offset:-4096
	global_load_dword v75, v3, s[34:35]
	s_waitcnt vmcnt(0)
	v_mul_f32_e32 v3, v76, v140
	v_fmac_f32_e32 v2, v3, v4
	v_mul_f32_e32 v3, v77, v141
	v_fmac_f32_e32 v2, v3, v5
	v_mul_f32_e32 v3, v78, v142
	v_fmac_f32_e32 v2, v3, v6
	v_mul_f32_e32 v3, v79, v143
	v_fmac_f32_e32 v2, v3, v7
	v_mul_f32_e32 v3, v80, v144
	v_fmac_f32_e32 v2, v3, v8
	v_mul_f32_e32 v3, v81, v145
	v_fmac_f32_e32 v2, v3, v9
	v_mul_f32_e32 v3, v82, v146
	v_fmac_f32_e32 v2, v3, v10
	v_mul_f32_e32 v3, v83, v147
	v_fmac_f32_e32 v2, v3, v11
	v_mul_f32_e32 v3, v84, v148
	v_fmac_f32_e32 v2, v3, v12
	v_mul_f32_e32 v3, v85, v149
	v_fmac_f32_e32 v2, v3, v13
	v_mul_f32_e32 v3, v86, v150
	v_fmac_f32_e32 v2, v3, v14
	v_mul_f32_e32 v3, v87, v151
	v_fmac_f32_e32 v2, v3, v15
	v_mul_f32_e32 v3, v88, v152
	v_fmac_f32_e32 v2, v3, v16
	v_mul_f32_e32 v3, v89, v153
	v_fmac_f32_e32 v2, v3, v17
	v_mul_f32_e32 v3, v90, v154
	v_fmac_f32_e32 v2, v3, v18
	v_mul_f32_e32 v3, v91, v155
	v_fmac_f32_e32 v2, v3, v19
	v_mul_f32_e32 v3, v92, v156
	v_fmac_f32_e32 v2, v3, v20
	v_mul_f32_e32 v3, v93, v157
	v_fmac_f32_e32 v2, v3, v21
	v_mul_f32_e32 v3, v94, v158
	v_fmac_f32_e32 v2, v3, v22
	v_mul_f32_e32 v3, v95, v159
	v_fmac_f32_e32 v2, v3, v23
	v_mul_f32_e32 v3, v96, v160
	v_fmac_f32_e32 v2, v3, v24
	v_mul_f32_e32 v3, v97, v161
	v_fmac_f32_e32 v2, v3, v25
	v_mul_f32_e32 v3, v98, v162
	v_fmac_f32_e32 v2, v3, v26
	v_mul_f32_e32 v3, v99, v163
	v_fmac_f32_e32 v2, v3, v27
	v_mul_f32_e32 v3, v100, v164
	v_fmac_f32_e32 v2, v3, v28
	v_mul_f32_e32 v3, v101, v165
	v_fmac_f32_e32 v2, v3, v29
	v_mul_f32_e32 v3, v102, v166
	v_fmac_f32_e32 v2, v3, v30
	v_mul_f32_e32 v3, v103, v167
	v_fmac_f32_e32 v2, v3, v31
	v_mul_f32_e32 v3, v104, v168
	v_fmac_f32_e32 v2, v3, v40
	v_mul_f32_e32 v3, v105, v169
	v_fmac_f32_e32 v2, v3, v41
	v_mul_f32_e32 v3, v106, v170
	v_fmac_f32_e32 v2, v3, v42
	v_mul_f32_e32 v3, v107, v171
	v_fmac_f32_e32 v2, v3, v43
	v_mul_f32_e32 v3, v108, v172
	v_fmac_f32_e32 v2, v3, v44
	v_mul_f32_e32 v3, v109, v173
	v_fmac_f32_e32 v2, v3, v45
	v_mul_f32_e32 v3, v110, v174
	v_fmac_f32_e32 v2, v3, v46
	v_mul_f32_e32 v3, v111, v175
	v_fmac_f32_e32 v2, v3, v47
	v_mul_f32_e32 v3, v112, v184
	v_fmac_f32_e32 v2, v3, v48
	v_mul_f32_e32 v3, v113, v185
	v_fmac_f32_e32 v2, v3, v49
	v_mul_f32_e32 v3, v114, v186
	v_fmac_f32_e32 v2, v3, v50
	v_mul_f32_e32 v3, v115, v187
	v_fmac_f32_e32 v2, v3, v51
	v_mul_f32_e32 v3, v116, v188
	v_fmac_f32_e32 v2, v3, v52
	v_mul_f32_e32 v3, v117, v189
	v_fmac_f32_e32 v2, v3, v53
	v_mul_f32_e32 v3, v118, v190
	v_fmac_f32_e32 v2, v3, v54
	v_mul_f32_e32 v3, v119, v191
	v_fmac_f32_e32 v2, v3, v55
	v_mul_f32_e32 v3, v120, v192
	v_fmac_f32_e32 v2, v3, v56
	v_mul_f32_e32 v3, v121, v193
	v_fmac_f32_e32 v2, v3, v57
	v_mul_f32_e32 v3, v122, v194
	v_fmac_f32_e32 v2, v3, v58
	v_mul_f32_e32 v3, v123, v195
	v_fmac_f32_e32 v2, v3, v59
	v_mul_f32_e32 v3, v124, v196
	v_fmac_f32_e32 v2, v3, v60
	v_mul_f32_e32 v3, v125, v197
	v_fmac_f32_e32 v2, v3, v61
	v_mul_f32_e32 v3, v126, v198
	v_fmac_f32_e32 v2, v3, v62
	v_mul_f32_e32 v3, v127, v199
	v_fmac_f32_e32 v2, v3, v63
	v_mul_f32_e32 v3, v128, v200
	v_fmac_f32_e32 v2, v3, v64
	v_mul_f32_e32 v3, v129, v201
	v_fmac_f32_e32 v2, v3, v65
	v_mul_f32_e32 v3, v130, v202
	v_fmac_f32_e32 v2, v3, v66
	v_mul_f32_e32 v3, v131, v203
	v_fmac_f32_e32 v2, v3, v67
	v_mul_f32_e32 v3, v132, v204
	v_fmac_f32_e32 v2, v3, v68
	v_mul_f32_e32 v3, v133, v205
	v_fmac_f32_e32 v2, v3, v69
	v_mul_f32_e32 v3, v134, v206
	v_fmac_f32_e32 v2, v3, v70
	v_mul_f32_e32 v3, v135, v207
	v_fmac_f32_e32 v2, v3, v71
	v_mul_f32_e32 v3, v136, v208
	v_fmac_f32_e32 v2, v3, v72
	v_mul_f32_e32 v3, v137, v209
	v_fmac_f32_e32 v2, v3, v73
	v_mul_f32_e32 v3, v138, v210
	v_fmac_f32_e32 v2, v3, v74
	v_mul_f32_e32 v3, v139, v211
	v_fmac_f32_e32 v2, v3, v75
	s_and_b32 s26, s30, 0xff
	s_lshl_b32 s27, s0, 6
	s_lshl_b32 s26, s26, 12
	s_lshl_b64 s[24:25], s[24:25], 20
	s_and_b32 s27, s27, 0x3c0
	s_or_b32 s24, s24, s26
	s_add_u32 s24, s65, s24
	v_or_b32_e32 v0, s27, v244
	s_addc_u32 s25, s66, s25
	s_add_i32 s0, s0, s2
	s_add_i32 s28, s28, s3
	v_lshlrev_b32_e32 v0, 2, v0
	s_cmpk_gt_i32 s0, 0x1fff
	global_store_dword v0, v2, s[24:25]
	s_cbranch_scc0 .LBB0_1174
